# S5 pass 2: stagger, waves 4-7 start the loop 768 cycles after their SIMD partners
# speedup vs baseline: 1.0019x; 1.0009x over previous
.LBB0_872:
	s_mov_b32 s30, 0x10000
	s_waitcnt vmcnt(3)
	v_add_co_u32_e32 v52, vcc, s30, v134
	s_mov_b32 s30, 0x20000
	s_nop 0
	v_addc_co_u32_e32 v53, vcc, 0, v135, vcc
	global_load_dwordx4 v[80:83], v[134:135], off
	global_load_dwordx4 v[76:79], v[52:53], off
	v_add_co_u32_e32 v52, vcc, s30, v134
	s_lshl_b32 s54, s50, 1
	s_nop 0
	v_addc_co_u32_e32 v53, vcc, 0, v135, vcc
	v_add_co_u32_e32 v54, vcc, 0x30000, v134
	v_mov_b32_e32 v127, v119
	s_nop 0
	v_addc_co_u32_e32 v55, vcc, 0, v135, vcc
	global_load_dwordx4 v[72:75], v[52:53], off
	global_load_dwordx4 v[68:71], v[54:55], off
	v_or_b32_e32 v52, s51, v137
	v_ashrrev_i32_e32 v53, 31, v52
	v_lshlrev_b64 v[52:53], 12, v[52:53]
	v_lshl_add_u64 v[52:53], s[58:59], 0, v[52:53]
	v_lshl_add_u64 v[52:53], v[52:53], 0, s[54:55]
	v_lshl_add_u64 v[84:85], v[52:53], 0, v[126:127]
	v_mov_b32_e32 v129, v128
	v_mov_b32_e32 v133, v132
	s_mov_b64 s[30:31], 0
	s_mov_b32 s54, -1
	s_bitcmp1_b32 s46, 0
	s_cbranch_scc0 .Lstag_p2
	s_sleep 12
.Lstag_p2:
	s_branch .LBB0_875
